# v52 with 'sc1 nt' (write-through + streaming) on GEMM1 epilogue stores
# baseline (speedup 1.0000x reference)
.LBB0_166:
	s_lshl_b32 s17, s89, 8
	s_add_i32 s17, s17, s61
	v_or_b32_e32 v152, s17, v1
	s_cmp_gt_i32 s88, 1
	s_mov_b64 s[18:19], -1
	s_cbranch_scc0 .LBB0_181
	s_cmp_gt_u32 s88, 3
	s_cbranch_scc0 .LBB0_177
	s_cmp_gt_u32 s88, 11
	s_cbranch_scc0 .LBB0_174
	s_cmp_gt_u32 s88, 19
	s_cbranch_scc0 .LBB0_171
	s_cmp_lt_u32 s88, 24
	s_cselect_b64 s[18:19], -1, 0
	s_and_b64 s[18:19], s[18:19], exec
	s_movk_i32 s18, 0xffec
	s_cselect_b32 s21, s18, 0xffffffe8
	s_mov_b32 s18, 0x8600000
	s_cselect_b32 s18, s18, 0xa600000
	s_add_u32 s18, s78, s18
	s_addc_u32 s19, s79, 0
	s_add_i32 s21, s21, s88
	v_lshl_or_b32 v166, s21, 8, v159
	v_ashrrev_i32_e32 v153, 31, v152
	v_lshlrev_b64 v[154:155], 11, v[152:153]
	v_ashrrev_i32_e32 v167, 31, v166
	v_lshl_add_u64 v[168:169], s[18:19], 0, v[154:155]
	v_lshlrev_b64 v[166:167], 1, v[166:167]
	v_cvt_pk_bf16_f32 v154, v126, v127
	v_cvt_pk_bf16_f32 v155, v128, v129
	v_cvt_pk_bf16_f32 v156, v122, v123
	v_cvt_pk_bf16_f32 v157, v124, v125
	v_lshl_add_u64 v[168:169], v[168:169], 0, v[166:167]
	global_store_dwordx4 v[168:169], v[154:157], off sc1 nt
	s_nop 1
	v_cvt_pk_bf16_f32 v154, v110, v111
	v_cvt_pk_bf16_f32 v155, v112, v113
	v_cvt_pk_bf16_f32 v156, v106, v107
	v_cvt_pk_bf16_f32 v157, v108, v109
	global_store_dwordx4 v[168:169], v[154:157], off offset:256 sc1 nt
	s_nop 1
	v_or_b32_e32 v154, 16, v152
	v_ashrrev_i32_e32 v155, 31, v154
	v_lshlrev_b64 v[154:155], 11, v[154:155]
	v_lshl_add_u64 v[170:171], s[18:19], 0, v[154:155]
	v_cvt_pk_bf16_f32 v154, v118, v119
	v_cvt_pk_bf16_f32 v155, v120, v121
	v_cvt_pk_bf16_f32 v156, v114, v115
	v_cvt_pk_bf16_f32 v157, v116, v117
	v_lshl_add_u64 v[170:171], v[170:171], 0, v[166:167]
	global_store_dwordx4 v[170:171], v[154:157], off sc1 nt
	s_nop 1
	v_cvt_pk_bf16_f32 v154, v94, v95
	v_cvt_pk_bf16_f32 v155, v96, v97
	v_cvt_pk_bf16_f32 v156, v90, v91
	v_cvt_pk_bf16_f32 v157, v92, v93
	global_store_dwordx4 v[170:171], v[154:157], off offset:256 sc1 nt
	s_nop 1
	v_or_b32_e32 v154, 32, v152
	v_ashrrev_i32_e32 v155, 31, v154
	v_lshlrev_b64 v[154:155], 11, v[154:155]
	v_lshl_add_u64 v[170:171], s[18:19], 0, v[154:155]
	v_cvt_pk_bf16_f32 v154, v102, v103
	v_cvt_pk_bf16_f32 v155, v104, v105
	v_cvt_pk_bf16_f32 v156, v98, v99
	v_cvt_pk_bf16_f32 v157, v100, v101
	v_lshl_add_u64 v[170:171], v[170:171], 0, v[166:167]
	global_store_dwordx4 v[170:171], v[154:157], off sc1 nt
	s_nop 1
	v_cvt_pk_bf16_f32 v154, v78, v79
	v_cvt_pk_bf16_f32 v155, v80, v81
	v_cvt_pk_bf16_f32 v156, v74, v75
	v_cvt_pk_bf16_f32 v157, v76, v77
	global_store_dwordx4 v[170:171], v[154:157], off offset:256 sc1 nt
	s_nop 1
	v_or_b32_e32 v154, 48, v152
	v_ashrrev_i32_e32 v155, 31, v154
	v_lshlrev_b64 v[154:155], 11, v[154:155]
	v_lshl_add_u64 v[170:171], s[18:19], 0, v[154:155]
	v_cvt_pk_bf16_f32 v154, v86, v87
	v_cvt_pk_bf16_f32 v155, v88, v89
	v_cvt_pk_bf16_f32 v156, v82, v83
	v_cvt_pk_bf16_f32 v157, v84, v85
	v_lshl_add_u64 v[166:167], v[170:171], 0, v[166:167]
	global_store_dwordx4 v[166:167], v[154:157], off sc1 nt
	v_add_co_u32_e32 v170, vcc, s84, v168
	s_nop 0
	v_cvt_pk_bf16_f32 v154, v70, v71
	v_cvt_pk_bf16_f32 v155, v72, v73
	v_cvt_pk_bf16_f32 v156, v66, v67
	v_cvt_pk_bf16_f32 v157, v68, v69
	global_store_dwordx4 v[166:167], v[154:157], off offset:256 sc1 nt
	s_mov_b64 s[18:19], 0x40000
	v_addc_co_u32_e32 v171, vcc, 0, v169, vcc
	v_cvt_pk_bf16_f32 v154, v62, v63
	v_cvt_pk_bf16_f32 v155, v64, v65
	v_cvt_pk_bf16_f32 v156, v58, v59
	v_cvt_pk_bf16_f32 v157, v60, v61
	v_lshl_add_u64 v[166:167], v[168:169], 0, s[18:19]
	global_store_dwordx4 v[170:171], v[154:157], off sc1 nt
	v_add_co_u32_e32 v170, vcc, s85, v168
	s_nop 0
	v_cvt_pk_bf16_f32 v154, v46, v47
	v_cvt_pk_bf16_f32 v155, v48, v49
	v_cvt_pk_bf16_f32 v156, v42, v43
	v_cvt_pk_bf16_f32 v157, v44, v45
	global_store_dwordx4 v[166:167], v[154:157], off offset:256 sc1 nt
	s_mov_b64 s[18:19], 0x48000
	v_addc_co_u32_e32 v171, vcc, 0, v169, vcc
	v_cvt_pk_bf16_f32 v154, v54, v55
	v_cvt_pk_bf16_f32 v155, v56, v57
	v_cvt_pk_bf16_f32 v156, v50, v51
	v_cvt_pk_bf16_f32 v157, v52, v53
	v_lshl_add_u64 v[166:167], v[168:169], 0, s[18:19]
	global_store_dwordx4 v[170:171], v[154:157], off sc1 nt
	v_add_co_u32_e32 v170, vcc, s86, v168
	s_nop 0
	v_cvt_pk_bf16_f32 v154, v30, v31
	v_cvt_pk_bf16_f32 v155, v32, v33
	v_cvt_pk_bf16_f32 v156, v26, v27
	v_cvt_pk_bf16_f32 v157, v28, v29
	global_store_dwordx4 v[166:167], v[154:157], off offset:256 sc1 nt
	s_mov_b64 s[18:19], 0x50000
	v_addc_co_u32_e32 v171, vcc, 0, v169, vcc
	v_cvt_pk_bf16_f32 v154, v38, v39
	v_cvt_pk_bf16_f32 v155, v40, v41
	v_cvt_pk_bf16_f32 v156, v34, v35
	v_cvt_pk_bf16_f32 v157, v36, v37
	v_lshl_add_u64 v[166:167], v[168:169], 0, s[18:19]
	global_store_dwordx4 v[170:171], v[154:157], off sc1 nt
	s_mov_b64 s[18:19], 0x58000
	s_nop 0
	v_cvt_pk_bf16_f32 v154, v14, v15
	v_cvt_pk_bf16_f32 v155, v16, v17
	v_cvt_pk_bf16_f32 v156, v10, v11
	v_cvt_pk_bf16_f32 v157, v12, v13
	global_store_dwordx4 v[166:167], v[154:157], off offset:256 sc1 nt
	v_lshl_add_u64 v[166:167], v[168:169], 0, s[18:19]
	s_mov_b32 s18, 0x58000
	v_add_co_u32_e32 v168, vcc, s18, v168
	v_cvt_pk_bf16_f32 v154, v22, v23
	v_cvt_pk_bf16_f32 v155, v24, v25
	v_cvt_pk_bf16_f32 v156, v18, v19
	v_cvt_pk_bf16_f32 v157, v20, v21
	v_addc_co_u32_e32 v169, vcc, 0, v169, vcc
	global_store_dwordx4 v[168:169], v[154:157], off sc1 nt
	s_mov_b64 s[18:19], 0
	s_nop 0
	v_cvt_pk_bf16_f32 v154, v6, v7
	v_cvt_pk_bf16_f32 v155, v8, v9
	v_cvt_pk_bf16_f32 v156, v2, v3
	v_cvt_pk_bf16_f32 v157, v4, v5
	global_store_dwordx4 v[166:167], v[154:157], off offset:256 sc1 nt
.LBB0_171:
	s_andn2_b64 vcc, exec, s[18:19]
	s_cbranch_vccnz .LBB0_173
	v_mul_f32_e32 v138, 0xbfb8aa3b, v110
	v_exp_f32_e32 v151, v138
	v_mul_f32_e32 v138, 0xbfb8aa3b, v111
	v_exp_f32_e32 v153, v138
	v_mul_f32_e32 v155, 0xbfb8aa3b, v113
	v_add_f32_e32 v151, 1.0, v151
	v_rcp_f32_e32 v154, v151
	v_add_f32_e32 v151, 1.0, v153
	v_mul_f32_e32 v153, 0xbfb8aa3b, v112
	v_exp_f32_e32 v153, v153
	v_exp_f32_e32 v157, v155
	v_rcp_f32_e32 v155, v151
	v_mul_f32_e32 v167, 0xbfb8aa3b, v109
	v_add_f32_e32 v151, 1.0, v153
	v_rcp_f32_e32 v156, v151
	v_add_f32_e32 v151, 1.0, v157
	v_rcp_f32_e32 v157, v151
	v_mul_f32_e32 v151, 0xbfb8aa3b, v106
	v_exp_f32_e32 v151, v151
	v_mul_f32_e32 v153, 0xbfb8aa3b, v107
	v_exp_f32_e32 v153, v153
	v_exp_f32_e32 v169, v167
	v_add_f32_e32 v151, 1.0, v151
	v_rcp_f32_e32 v166, v151
	v_add_f32_e32 v151, 1.0, v153
	v_mul_f32_e32 v153, 0xbfb8aa3b, v108
	v_exp_f32_e32 v153, v153
	v_rcp_f32_e32 v167, v151
	v_pk_mul_f32 v[156:157], v[112:113], v[156:157]
	v_lshl_add_u32 v138, s88, 7, v160
	v_add_f32_e32 v151, 1.0, v153
	v_rcp_f32_e32 v168, v151
	v_add_f32_e32 v151, 1.0, v169
	v_rcp_f32_e32 v169, v151
	v_pk_mul_f32 v[156:157], v[128:129], v[156:157]
	v_pk_mul_f32 v[166:167], v[106:107], v[166:167]
	v_pk_mul_f32 v[154:155], v[110:111], v[154:155]
	v_pk_mul_f32 v[168:169], v[108:109], v[168:169]
	v_mul_f32_e32 v151, 0xbfb8aa3b, v95
	v_pk_mul_f32 v[170:171], v[124:125], v[168:169]
	v_pk_mul_f32 v[168:169], v[122:123], v[166:167]
	v_cvt_pk_bf16_f32 v167, v156, v157
	v_lshlrev_b64 v[156:157], 1, v[138:139]
	v_mul_f32_e32 v138, 0xbfb8aa3b, v94
	v_exp_f32_e32 v138, v138
	v_pk_mul_f32 v[154:155], v[126:127], v[154:155]
	v_ashrrev_i32_e32 v153, 31, v152
	v_exp_f32_e32 v151, v151
	v_cvt_pk_bf16_f32 v166, v154, v155
	v_lshlrev_b64 v[154:155], 11, v[152:153]
	v_lshl_add_u64 v[154:155], s[10:11], 0, v[154:155]
	v_cvt_pk_bf16_f32 v168, v168, v169
	v_cvt_pk_bf16_f32 v169, v170, v171
	v_lshl_add_u64 v[154:155], v[154:155], 0, v[156:157]
	v_add_f32_e32 v138, 1.0, v138
	global_store_dwordx4 v[154:155], v[166:169], off sc1 nt
	v_mul_f32_e32 v153, 0xbfb8aa3b, v97
	v_exp_f32_e32 v153, v153
	v_rcp_f32_e32 v166, v138
	v_add_f32_e32 v138, 1.0, v151
	v_mul_f32_e32 v151, 0xbfb8aa3b, v96
	v_exp_f32_e32 v151, v151
	v_rcp_f32_e32 v167, v138
	v_or_b32_e32 v170, 16, v152
	v_ashrrev_i32_e32 v171, 31, v170
	v_add_f32_e32 v138, 1.0, v151
	v_rcp_f32_e32 v168, v138
	v_add_f32_e32 v138, 1.0, v153
	v_rcp_f32_e32 v169, v138
	v_mul_f32_e32 v138, 0xbfb8aa3b, v90
	v_exp_f32_e32 v138, v138
	v_mul_f32_e32 v151, 0xbfb8aa3b, v91
	v_exp_f32_e32 v151, v151
	v_mul_f32_e32 v153, 0xbfb8aa3b, v93
	v_add_f32_e32 v138, 1.0, v138
	v_rcp_f32_e32 v172, v138
	v_add_f32_e32 v138, 1.0, v151
	v_mul_f32_e32 v151, 0xbfb8aa3b, v92
	v_exp_f32_e32 v151, v151
	v_exp_f32_e32 v153, v153
	v_rcp_f32_e32 v173, v138
	v_pk_mul_f32 v[166:167], v[94:95], v[166:167]
	v_add_f32_e32 v138, 1.0, v151
	v_rcp_f32_e32 v174, v138
	v_add_f32_e32 v138, 1.0, v153
	v_rcp_f32_e32 v175, v138
	v_mul_f32_e32 v138, 0xbfb8aa3b, v78
	v_exp_f32_e32 v138, v138
	v_mul_f32_e32 v151, 0xbfb8aa3b, v79
	v_exp_f32_e32 v151, v151
	v_pk_mul_f32 v[168:169], v[96:97], v[168:169]
	v_pk_mul_f32 v[172:173], v[90:91], v[172:173]
	v_pk_mul_f32 v[174:175], v[92:93], v[174:175]
	v_lshlrev_b64 v[170:171], 11, v[170:171]
	v_pk_mul_f32 v[168:169], v[120:121], v[168:169]
	v_pk_mul_f32 v[166:167], v[118:119], v[166:167]
	v_pk_mul_f32 v[174:175], v[116:117], v[174:175]
	v_pk_mul_f32 v[172:173], v[114:115], v[172:173]
	v_lshl_add_u64 v[170:171], s[10:11], 0, v[170:171]
	v_cvt_pk_bf16_f32 v166, v166, v167
	v_cvt_pk_bf16_f32 v167, v168, v169
	v_cvt_pk_bf16_f32 v168, v172, v173
	v_cvt_pk_bf16_f32 v169, v174, v175
	v_lshl_add_u64 v[170:171], v[170:171], 0, v[156:157]
	v_add_f32_e32 v138, 1.0, v138
	global_store_dwordx4 v[170:171], v[166:169], off sc1 nt
	v_mul_f32_e32 v153, 0xbfb8aa3b, v81
	v_exp_f32_e32 v153, v153
	v_rcp_f32_e32 v166, v138
	v_add_f32_e32 v138, 1.0, v151
	v_mul_f32_e32 v151, 0xbfb8aa3b, v80
	v_exp_f32_e32 v151, v151
	v_rcp_f32_e32 v167, v138
	v_or_b32_e32 v170, 32, v152
	v_ashrrev_i32_e32 v171, 31, v170
	v_add_f32_e32 v138, 1.0, v151
	v_rcp_f32_e32 v168, v138
	v_add_f32_e32 v138, 1.0, v153
	v_rcp_f32_e32 v169, v138
	v_mul_f32_e32 v138, 0xbfb8aa3b, v74
	v_exp_f32_e32 v138, v138
	v_mul_f32_e32 v151, 0xbfb8aa3b, v75
	v_exp_f32_e32 v151, v151
	v_mul_f32_e32 v153, 0xbfb8aa3b, v77
	v_add_f32_e32 v138, 1.0, v138
	v_rcp_f32_e32 v172, v138
	v_add_f32_e32 v138, 1.0, v151
	v_mul_f32_e32 v151, 0xbfb8aa3b, v76
	v_exp_f32_e32 v151, v151
	v_exp_f32_e32 v153, v153
	v_rcp_f32_e32 v173, v138
	v_pk_mul_f32 v[166:167], v[78:79], v[166:167]
	v_add_f32_e32 v138, 1.0, v151
	v_rcp_f32_e32 v174, v138
	v_add_f32_e32 v138, 1.0, v153
	v_rcp_f32_e32 v175, v138
	v_mul_f32_e32 v138, 0xbfb8aa3b, v70
	v_exp_f32_e32 v138, v138
	v_mul_f32_e32 v151, 0xbfb8aa3b, v71
	v_exp_f32_e32 v151, v151
	v_pk_mul_f32 v[168:169], v[80:81], v[168:169]
	v_pk_mul_f32 v[172:173], v[74:75], v[172:173]
	v_pk_mul_f32 v[174:175], v[76:77], v[174:175]
	v_lshlrev_b64 v[170:171], 11, v[170:171]
	v_pk_mul_f32 v[168:169], v[104:105], v[168:169]
	v_pk_mul_f32 v[166:167], v[102:103], v[166:167]
	v_pk_mul_f32 v[174:175], v[100:101], v[174:175]
	v_pk_mul_f32 v[172:173], v[98:99], v[172:173]
	v_lshl_add_u64 v[170:171], s[10:11], 0, v[170:171]
	v_cvt_pk_bf16_f32 v166, v166, v167
	v_cvt_pk_bf16_f32 v167, v168, v169
	v_cvt_pk_bf16_f32 v168, v172, v173
	v_cvt_pk_bf16_f32 v169, v174, v175
	v_lshl_add_u64 v[170:171], v[170:171], 0, v[156:157]
	v_add_f32_e32 v138, 1.0, v138
	global_store_dwordx4 v[170:171], v[166:169], off sc1 nt
	v_mul_f32_e32 v153, 0xbfb8aa3b, v73
	v_exp_f32_e32 v153, v153
	v_rcp_f32_e32 v166, v138
	v_add_f32_e32 v138, 1.0, v151
	v_mul_f32_e32 v151, 0xbfb8aa3b, v72
	v_exp_f32_e32 v151, v151
	v_rcp_f32_e32 v167, v138
	v_or_b32_e32 v170, 48, v152
	v_ashrrev_i32_e32 v171, 31, v170
	v_add_f32_e32 v138, 1.0, v151
	v_rcp_f32_e32 v168, v138
	v_add_f32_e32 v138, 1.0, v153
	v_rcp_f32_e32 v169, v138
	v_mul_f32_e32 v138, 0xbfb8aa3b, v66
	v_exp_f32_e32 v138, v138
	v_mul_f32_e32 v151, 0xbfb8aa3b, v67
	v_exp_f32_e32 v151, v151
	v_mul_f32_e32 v153, 0xbfb8aa3b, v69
	v_add_f32_e32 v138, 1.0, v138
	v_rcp_f32_e32 v172, v138
	v_add_f32_e32 v138, 1.0, v151
	v_mul_f32_e32 v151, 0xbfb8aa3b, v68
	v_exp_f32_e32 v151, v151
	v_exp_f32_e32 v153, v153
	v_rcp_f32_e32 v173, v138
	v_pk_mul_f32 v[166:167], v[70:71], v[166:167]
	v_add_f32_e32 v138, 1.0, v151
	v_rcp_f32_e32 v174, v138
	v_add_f32_e32 v138, 1.0, v153
	v_rcp_f32_e32 v175, v138
	v_mul_f32_e32 v138, 0xbfb8aa3b, v46
	v_exp_f32_e32 v138, v138
	v_mul_f32_e32 v151, 0xbfb8aa3b, v47
	v_exp_f32_e32 v151, v151
	v_pk_mul_f32 v[168:169], v[72:73], v[168:169]
	v_pk_mul_f32 v[172:173], v[66:67], v[172:173]
	v_pk_mul_f32 v[174:175], v[68:69], v[174:175]
	v_lshlrev_b64 v[170:171], 11, v[170:171]
	v_pk_mul_f32 v[168:169], v[88:89], v[168:169]
	v_pk_mul_f32 v[166:167], v[86:87], v[166:167]
	v_pk_mul_f32 v[174:175], v[84:85], v[174:175]
	v_pk_mul_f32 v[172:173], v[82:83], v[172:173]
	v_lshl_add_u64 v[170:171], s[10:11], 0, v[170:171]
	v_cvt_pk_bf16_f32 v166, v166, v167
	v_cvt_pk_bf16_f32 v167, v168, v169
	v_cvt_pk_bf16_f32 v168, v172, v173
	v_cvt_pk_bf16_f32 v169, v174, v175
	v_lshl_add_u64 v[156:157], v[170:171], 0, v[156:157]
	v_add_f32_e32 v138, 1.0, v138
	global_store_dwordx4 v[156:157], v[166:169], off sc1 nt
	v_rcp_f32_e32 v156, v138
	v_add_f32_e32 v138, 1.0, v151
	v_mul_f32_e32 v151, 0xbfb8aa3b, v48
	v_exp_f32_e32 v151, v151
	v_mul_f32_e32 v153, 0xbfb8aa3b, v49
	v_exp_f32_e32 v153, v153
	v_rcp_f32_e32 v157, v138
	v_add_f32_e32 v138, 1.0, v151
	v_rcp_f32_e32 v166, v138
	v_add_f32_e32 v138, 1.0, v153
	v_rcp_f32_e32 v167, v138
	v_mul_f32_e32 v138, 0xbfb8aa3b, v42
	v_exp_f32_e32 v138, v138
	v_mul_f32_e32 v151, 0xbfb8aa3b, v43
	v_exp_f32_e32 v151, v151
	v_mul_f32_e32 v153, 0xbfb8aa3b, v45
	v_add_f32_e32 v138, 1.0, v138
	v_rcp_f32_e32 v168, v138
	v_add_f32_e32 v138, 1.0, v151
	v_mul_f32_e32 v151, 0xbfb8aa3b, v44
	v_exp_f32_e32 v151, v151
	v_exp_f32_e32 v153, v153
	v_rcp_f32_e32 v169, v138
	v_pk_mul_f32 v[156:157], v[46:47], v[156:157]
	v_add_f32_e32 v138, 1.0, v151
	v_rcp_f32_e32 v170, v138
	v_add_f32_e32 v138, 1.0, v153
	v_rcp_f32_e32 v171, v138
	v_mul_f32_e32 v138, 0xbfb8aa3b, v30
	v_exp_f32_e32 v138, v138
	v_mul_f32_e32 v151, 0xbfb8aa3b, v31
	v_pk_mul_f32 v[166:167], v[48:49], v[166:167]
	v_exp_f32_e32 v151, v151
	v_pk_mul_f32 v[172:173], v[64:65], v[166:167]
	v_pk_mul_f32 v[156:157], v[62:63], v[156:157]
	v_pk_mul_f32 v[166:167], v[42:43], v[168:169]
	v_pk_mul_f32 v[168:169], v[44:45], v[170:171]
	v_add_f32_e32 v138, 1.0, v138
	v_pk_mul_f32 v[170:171], v[60:61], v[168:169]
	v_pk_mul_f32 v[168:169], v[58:59], v[166:167]
	v_cvt_pk_bf16_f32 v166, v156, v157
	v_add_co_u32_e32 v156, vcc, s84, v154
	v_cvt_pk_bf16_f32 v167, v172, v173
	v_cvt_pk_bf16_f32 v168, v168, v169
	v_cvt_pk_bf16_f32 v169, v170, v171
	v_addc_co_u32_e32 v157, vcc, 0, v155, vcc
	global_store_dwordx4 v[156:157], v[166:169], off sc1 nt
	v_rcp_f32_e32 v156, v138
	v_add_f32_e32 v138, 1.0, v151
	v_mul_f32_e32 v151, 0xbfb8aa3b, v32
	v_exp_f32_e32 v151, v151
	v_mul_f32_e32 v153, 0xbfb8aa3b, v33
	v_exp_f32_e32 v153, v153
	v_rcp_f32_e32 v157, v138
	v_add_f32_e32 v138, 1.0, v151
	v_rcp_f32_e32 v166, v138
	v_add_f32_e32 v138, 1.0, v153
	v_rcp_f32_e32 v167, v138
	v_mul_f32_e32 v138, 0xbfb8aa3b, v26
	v_exp_f32_e32 v138, v138
	v_mul_f32_e32 v151, 0xbfb8aa3b, v27
	v_exp_f32_e32 v151, v151
	v_mul_f32_e32 v153, 0xbfb8aa3b, v29
	v_add_f32_e32 v138, 1.0, v138
	v_rcp_f32_e32 v168, v138
	v_add_f32_e32 v138, 1.0, v151
	v_mul_f32_e32 v151, 0xbfb8aa3b, v28
	v_exp_f32_e32 v151, v151
	v_exp_f32_e32 v153, v153
	v_rcp_f32_e32 v169, v138
	v_pk_mul_f32 v[156:157], v[30:31], v[156:157]
	v_add_f32_e32 v138, 1.0, v151
	v_rcp_f32_e32 v170, v138
	v_add_f32_e32 v138, 1.0, v153
	v_rcp_f32_e32 v171, v138
	v_mul_f32_e32 v138, 0xbfb8aa3b, v14
	v_exp_f32_e32 v138, v138
	v_mul_f32_e32 v151, 0xbfb8aa3b, v15
	v_pk_mul_f32 v[166:167], v[32:33], v[166:167]
	v_exp_f32_e32 v151, v151
	v_pk_mul_f32 v[172:173], v[56:57], v[166:167]
	v_pk_mul_f32 v[156:157], v[54:55], v[156:157]
	v_pk_mul_f32 v[166:167], v[26:27], v[168:169]
	v_pk_mul_f32 v[168:169], v[28:29], v[170:171]
	v_add_f32_e32 v138, 1.0, v138
	v_pk_mul_f32 v[170:171], v[52:53], v[168:169]
	v_pk_mul_f32 v[168:169], v[50:51], v[166:167]
	v_cvt_pk_bf16_f32 v166, v156, v157
	v_add_co_u32_e32 v156, vcc, s85, v154
	v_cvt_pk_bf16_f32 v167, v172, v173
	v_cvt_pk_bf16_f32 v168, v168, v169
	v_cvt_pk_bf16_f32 v169, v170, v171
	v_addc_co_u32_e32 v157, vcc, 0, v155, vcc
	global_store_dwordx4 v[156:157], v[166:169], off sc1 nt
	v_rcp_f32_e32 v156, v138
	v_add_f32_e32 v138, 1.0, v151
	v_mul_f32_e32 v151, 0xbfb8aa3b, v16
	v_exp_f32_e32 v151, v151
	v_mul_f32_e32 v153, 0xbfb8aa3b, v17
	v_exp_f32_e32 v153, v153
	v_rcp_f32_e32 v157, v138
	v_add_f32_e32 v138, 1.0, v151
	v_rcp_f32_e32 v166, v138
	v_add_f32_e32 v138, 1.0, v153
	v_rcp_f32_e32 v167, v138
	v_mul_f32_e32 v138, 0xbfb8aa3b, v10
	v_exp_f32_e32 v138, v138
	v_mul_f32_e32 v151, 0xbfb8aa3b, v11
	v_exp_f32_e32 v151, v151
	v_mul_f32_e32 v153, 0xbfb8aa3b, v13
	v_add_f32_e32 v138, 1.0, v138
	v_rcp_f32_e32 v168, v138
	v_add_f32_e32 v138, 1.0, v151
	v_mul_f32_e32 v151, 0xbfb8aa3b, v12
	v_exp_f32_e32 v151, v151
	v_exp_f32_e32 v153, v153
	v_rcp_f32_e32 v169, v138
	v_pk_mul_f32 v[156:157], v[14:15], v[156:157]
	v_add_f32_e32 v138, 1.0, v151
	v_rcp_f32_e32 v170, v138
	v_add_f32_e32 v138, 1.0, v153
	v_rcp_f32_e32 v171, v138
	v_mul_f32_e32 v138, 0xbfb8aa3b, v6
	v_exp_f32_e32 v138, v138
	v_mul_f32_e32 v151, 0xbfb8aa3b, v7
	v_pk_mul_f32 v[166:167], v[16:17], v[166:167]
	v_exp_f32_e32 v151, v151
	v_pk_mul_f32 v[172:173], v[40:41], v[166:167]
	v_pk_mul_f32 v[156:157], v[38:39], v[156:157]
	v_pk_mul_f32 v[166:167], v[10:11], v[168:169]
	v_pk_mul_f32 v[168:169], v[12:13], v[170:171]
	v_add_f32_e32 v138, 1.0, v138
	v_pk_mul_f32 v[170:171], v[36:37], v[168:169]
	v_pk_mul_f32 v[168:169], v[34:35], v[166:167]
	v_cvt_pk_bf16_f32 v166, v156, v157
	v_add_co_u32_e32 v156, vcc, s86, v154
	v_cvt_pk_bf16_f32 v167, v172, v173
	v_cvt_pk_bf16_f32 v168, v168, v169
	v_cvt_pk_bf16_f32 v169, v170, v171
	v_addc_co_u32_e32 v157, vcc, 0, v155, vcc
	global_store_dwordx4 v[156:157], v[166:169], off sc1 nt
	v_rcp_f32_e32 v156, v138
	v_add_f32_e32 v138, 1.0, v151
	v_mul_f32_e32 v151, 0xbfb8aa3b, v8
	v_exp_f32_e32 v151, v151
	v_mul_f32_e32 v153, 0xbfb8aa3b, v9
	v_exp_f32_e32 v153, v153
	v_rcp_f32_e32 v157, v138
	v_add_f32_e32 v138, 1.0, v151
	v_rcp_f32_e32 v166, v138
	v_add_f32_e32 v138, 1.0, v153
	v_rcp_f32_e32 v167, v138
	v_mul_f32_e32 v138, 0xbfb8aa3b, v2
	v_exp_f32_e32 v138, v138
	v_mul_f32_e32 v151, 0xbfb8aa3b, v3
	v_exp_f32_e32 v151, v151
	v_mul_f32_e32 v153, 0xbfb8aa3b, v5
	v_add_f32_e32 v138, 1.0, v138
	v_rcp_f32_e32 v168, v138
	v_add_f32_e32 v138, 1.0, v151
	v_mul_f32_e32 v151, 0xbfb8aa3b, v4
	v_exp_f32_e32 v151, v151
	v_exp_f32_e32 v153, v153
	v_rcp_f32_e32 v169, v138
	v_pk_mul_f32 v[166:167], v[8:9], v[166:167]
	v_add_f32_e32 v138, 1.0, v151
	v_rcp_f32_e32 v170, v138
	v_add_f32_e32 v138, 1.0, v153
	v_rcp_f32_e32 v171, v138
	v_pk_mul_f32 v[156:157], v[6:7], v[156:157]
	v_pk_mul_f32 v[172:173], v[24:25], v[166:167]
	v_pk_mul_f32 v[166:167], v[2:3], v[168:169]
	v_pk_mul_f32 v[168:169], v[4:5], v[170:171]
	v_pk_mul_f32 v[156:157], v[22:23], v[156:157]
	v_pk_mul_f32 v[170:171], v[20:21], v[168:169]
	v_pk_mul_f32 v[168:169], v[18:19], v[166:167]
	v_add_co_u32_e32 v154, vcc, 0x58000, v154
	v_cvt_pk_bf16_f32 v166, v156, v157
	v_cvt_pk_bf16_f32 v167, v172, v173
	v_cvt_pk_bf16_f32 v168, v168, v169
	v_cvt_pk_bf16_f32 v169, v170, v171
	v_addc_co_u32_e32 v155, vcc, 0, v155, vcc
	global_store_dwordx4 v[154:155], v[166:169], off sc1 nt

.LBB0_174:
	s_andn2_b64 vcc, exec, s[18:19]
	s_cbranch_vccnz .LBB0_176
	v_pk_mul_f32 v[156:157], v[128:129], v[112:113]
	v_pk_mul_f32 v[154:155], v[126:127], v[110:111]
	v_pk_mul_f32 v[166:167], v[124:125], v[108:109]
	v_ashrrev_i32_e32 v153, 31, v152
	v_lshl_add_u32 v138, s88, 7, v161
	v_pk_mul_f32 v[168:169], v[122:123], v[106:107]
	v_cvt_pk_bf16_f32 v154, v154, v155
	v_cvt_pk_bf16_f32 v155, v156, v157
	v_cvt_pk_bf16_f32 v157, v166, v167
	v_lshlrev_b64 v[166:167], 11, v[152:153]
	v_or_b32_e32 v170, 16, v152
	v_cvt_pk_bf16_f32 v156, v168, v169
	v_lshl_add_u64 v[166:167], s[34:35], 0, v[166:167]
	v_lshlrev_b64 v[168:169], 1, v[138:139]
	v_ashrrev_i32_e32 v171, 31, v170
	v_lshl_add_u64 v[166:167], v[166:167], 0, v[168:169]
	v_lshlrev_b64 v[170:171], 11, v[170:171]
	global_store_dwordx4 v[166:167], v[154:157], off sc1 nt
	v_pk_mul_f32 v[172:173], v[116:117], v[92:93]
	v_pk_mul_f32 v[174:175], v[114:115], v[90:91]
	v_pk_mul_f32 v[156:157], v[120:121], v[96:97]
	v_pk_mul_f32 v[154:155], v[118:119], v[94:95]
	v_lshl_add_u64 v[170:171], s[34:35], 0, v[170:171]
	v_cvt_pk_bf16_f32 v154, v154, v155
	v_cvt_pk_bf16_f32 v155, v156, v157
	v_cvt_pk_bf16_f32 v156, v174, v175
	v_cvt_pk_bf16_f32 v157, v172, v173
	v_lshl_add_u64 v[170:171], v[170:171], 0, v[168:169]
	global_store_dwordx4 v[170:171], v[154:157], off sc1 nt
	v_or_b32_e32 v170, 32, v152
	v_ashrrev_i32_e32 v171, 31, v170
	v_lshlrev_b64 v[170:171], 11, v[170:171]
	v_pk_mul_f32 v[156:157], v[104:105], v[80:81]
	v_pk_mul_f32 v[154:155], v[102:103], v[78:79]
	v_pk_mul_f32 v[172:173], v[100:101], v[76:77]
	v_pk_mul_f32 v[174:175], v[98:99], v[74:75]
	v_lshl_add_u64 v[170:171], s[34:35], 0, v[170:171]
	v_cvt_pk_bf16_f32 v154, v154, v155
	v_cvt_pk_bf16_f32 v155, v156, v157
	v_cvt_pk_bf16_f32 v156, v174, v175
	v_cvt_pk_bf16_f32 v157, v172, v173
	v_lshl_add_u64 v[170:171], v[170:171], 0, v[168:169]
	global_store_dwordx4 v[170:171], v[154:157], off sc1 nt
	v_or_b32_e32 v170, 48, v152
	v_ashrrev_i32_e32 v171, 31, v170
	v_lshlrev_b64 v[170:171], 11, v[170:171]
	v_pk_mul_f32 v[156:157], v[88:89], v[72:73]
	v_pk_mul_f32 v[154:155], v[86:87], v[70:71]
	v_pk_mul_f32 v[172:173], v[84:85], v[68:69]
	v_pk_mul_f32 v[174:175], v[82:83], v[66:67]
	v_lshl_add_u64 v[170:171], s[34:35], 0, v[170:171]
	v_cvt_pk_bf16_f32 v154, v154, v155
	v_cvt_pk_bf16_f32 v155, v156, v157
	v_cvt_pk_bf16_f32 v156, v174, v175
	v_cvt_pk_bf16_f32 v157, v172, v173
	v_lshl_add_u64 v[168:169], v[170:171], 0, v[168:169]
	global_store_dwordx4 v[168:169], v[154:157], off sc1 nt
	v_pk_mul_f32 v[168:169], v[60:61], v[44:45]
	v_pk_mul_f32 v[170:171], v[58:59], v[42:43]
	v_pk_mul_f32 v[156:157], v[64:65], v[48:49]
	v_pk_mul_f32 v[154:155], v[62:63], v[46:47]
	s_nop 0
	v_cvt_pk_bf16_f32 v154, v154, v155
	v_cvt_pk_bf16_f32 v155, v156, v157
	v_cvt_pk_bf16_f32 v157, v168, v169
	v_add_co_u32_e32 v168, vcc, s84, v166
	v_cvt_pk_bf16_f32 v156, v170, v171
	s_nop 0
	v_addc_co_u32_e32 v169, vcc, 0, v167, vcc
	global_store_dwordx4 v[168:169], v[154:157], off sc1 nt
	v_pk_mul_f32 v[168:169], v[52:53], v[28:29]
	v_pk_mul_f32 v[170:171], v[50:51], v[26:27]
	v_pk_mul_f32 v[156:157], v[56:57], v[32:33]
	v_pk_mul_f32 v[154:155], v[54:55], v[30:31]
	s_nop 0
	v_cvt_pk_bf16_f32 v154, v154, v155
	v_cvt_pk_bf16_f32 v155, v156, v157
	v_cvt_pk_bf16_f32 v157, v168, v169
	v_add_co_u32_e32 v168, vcc, s85, v166
	v_cvt_pk_bf16_f32 v156, v170, v171
	s_nop 0
	v_addc_co_u32_e32 v169, vcc, 0, v167, vcc
	global_store_dwordx4 v[168:169], v[154:157], off sc1 nt
	v_pk_mul_f32 v[168:169], v[36:37], v[12:13]
	v_pk_mul_f32 v[170:171], v[34:35], v[10:11]
	v_pk_mul_f32 v[156:157], v[40:41], v[16:17]
	v_pk_mul_f32 v[154:155], v[38:39], v[14:15]
	s_nop 0
	v_cvt_pk_bf16_f32 v154, v154, v155
	v_cvt_pk_bf16_f32 v155, v156, v157
	v_cvt_pk_bf16_f32 v157, v168, v169
	v_add_co_u32_e32 v168, vcc, s86, v166
	v_cvt_pk_bf16_f32 v156, v170, v171
	s_nop 0
	v_addc_co_u32_e32 v169, vcc, 0, v167, vcc
	global_store_dwordx4 v[168:169], v[154:157], off sc1 nt
	v_pk_mul_f32 v[168:169], v[20:21], v[4:5]
	v_pk_mul_f32 v[170:171], v[18:19], v[2:3]
	v_pk_mul_f32 v[156:157], v[24:25], v[8:9]
	v_pk_mul_f32 v[154:155], v[22:23], v[6:7]
	v_add_co_u32_e32 v166, vcc, 0x58000, v166
	v_cvt_pk_bf16_f32 v154, v154, v155
	v_cvt_pk_bf16_f32 v155, v156, v157
	v_cvt_pk_bf16_f32 v156, v170, v171
	v_cvt_pk_bf16_f32 v157, v168, v169
	v_addc_co_u32_e32 v167, vcc, 0, v167, vcc
	global_store_dwordx4 v[166:167], v[154:157], off sc1 nt

.LBB0_177:
	s_andn2_b64 vcc, exec, s[18:19]
	s_cbranch_vccnz .LBB0_179
	v_mul_f32_e32 v138, 0xbfb8aa3b, v126
	v_ashrrev_i32_e32 v153, 31, v152
	v_exp_f32_e32 v151, v138
	v_lshlrev_b64 v[154:155], 10, v[152:153]
	v_mul_f32_e32 v153, 0xbfb8aa3b, v127
	v_exp_f32_e32 v153, v153
	v_mul_f32_e32 v156, 0xbfb8aa3b, v128
	v_exp_f32_e32 v166, v156
	v_add_f32_e32 v151, 1.0, v151
	v_rcp_f32_e32 v156, v151
	v_add_f32_e32 v151, 1.0, v153
	v_mul_f32_e32 v153, 0xbfb8aa3b, v129
	v_rcp_f32_e32 v157, v151
	v_add_f32_e32 v151, 1.0, v166
	v_exp_f32_e32 v153, v153
	v_mul_f32_e32 v166, 0xbfb8aa3b, v122
	v_exp_f32_e32 v168, v166
	v_rcp_f32_e32 v166, v151
	v_add_f32_e32 v151, 1.0, v153
	v_rcp_f32_e32 v167, v151
	v_add_f32_e32 v151, 1.0, v168
	v_rcp_f32_e32 v168, v151
	v_mul_f32_e32 v151, 0xbfb8aa3b, v123
	v_mul_f32_e32 v153, 0xbfb8aa3b, v124
	v_exp_f32_e32 v151, v151
	v_exp_f32_e32 v153, v153
	v_mul_f32_e32 v169, 0xbfb8aa3b, v125
	v_exp_f32_e32 v169, v169
	v_add_f32_e32 v151, 1.0, v151
	v_add_f32_e32 v153, 1.0, v153
	v_rcp_f32_e32 v170, v153
	v_add_f32_e32 v153, 1.0, v169
	v_rcp_f32_e32 v169, v151
	v_mul_f32_e32 v151, 0xbfb8aa3b, v110
	v_exp_f32_e32 v151, v151
	v_lshl_add_u32 v138, s88, 8, v161
	v_rcp_f32_e32 v171, v153
	v_pk_mul_f32 v[156:157], v[126:127], v[156:157]
	v_pk_mul_f32 v[172:173], v[128:129], v[166:167]
	v_cvt_pk_bf16_f32 v166, v156, v157
	v_lshlrev_b64 v[156:157], 1, v[138:139]
	v_add_f32_e32 v138, 1.0, v151
	v_mul_f32_e32 v151, 0xbfb8aa3b, v111
	v_exp_f32_e32 v151, v151
	v_mul_f32_e32 v153, 0xbfb8aa3b, v112
	v_exp_f32_e32 v153, v153
	v_pk_mul_f32 v[170:171], v[124:125], v[170:171]
	v_pk_mul_f32 v[168:169], v[122:123], v[168:169]
	v_lshl_add_u64 v[154:155], s[8:9], 0, v[154:155]
	v_cvt_pk_bf16_f32 v167, v172, v173
	v_cvt_pk_bf16_f32 v168, v168, v169
	v_cvt_pk_bf16_f32 v169, v170, v171
	v_lshl_add_u64 v[154:155], v[154:155], 0, v[156:157]
	global_store_dwordx4 v[154:155], v[166:169], off sc1 nt
	s_mov_b64 s[18:19], 0x20000
	s_nop 0
	v_rcp_f32_e32 v166, v138
	v_add_f32_e32 v138, 1.0, v151
	v_mul_f32_e32 v151, 0xbfb8aa3b, v113
	v_rcp_f32_e32 v167, v138
	v_add_f32_e32 v138, 1.0, v153
	v_exp_f32_e32 v151, v151
	v_mul_f32_e32 v153, 0xbfb8aa3b, v106
	v_exp_f32_e32 v153, v153
	v_rcp_f32_e32 v168, v138
	v_add_f32_e32 v138, 1.0, v151
	v_rcp_f32_e32 v169, v138
	v_add_f32_e32 v138, 1.0, v153
	v_mul_f32_e32 v151, 0xbfb8aa3b, v108
	v_rcp_f32_e32 v170, v138
	v_mul_f32_e32 v138, 0xbfb8aa3b, v107
	v_exp_f32_e32 v151, v151
	v_mul_f32_e32 v153, 0xbfb8aa3b, v109
	v_exp_f32_e32 v138, v138
	v_exp_f32_e32 v153, v153
	v_add_f32_e32 v151, 1.0, v151
	v_rcp_f32_e32 v172, v151
	v_add_f32_e32 v138, 1.0, v138
	v_add_f32_e32 v151, 1.0, v153
	v_rcp_f32_e32 v173, v151
	v_rcp_f32_e32 v171, v138
	v_mul_f32_e32 v138, 0xbfb8aa3b, v118
	v_exp_f32_e32 v138, v138
	v_mul_f32_e32 v151, 0xbfb8aa3b, v119
	v_pk_mul_f32 v[168:169], v[112:113], v[168:169]
	v_pk_mul_f32 v[166:167], v[110:111], v[166:167]
	v_pk_mul_f32 v[172:173], v[108:109], v[172:173]
	v_pk_mul_f32 v[170:171], v[106:107], v[170:171]
	v_exp_f32_e32 v151, v151
	v_mul_f32_e32 v153, 0xbfb8aa3b, v120
	v_cvt_pk_bf16_f32 v166, v166, v167
	v_cvt_pk_bf16_f32 v167, v168, v169
	v_cvt_pk_bf16_f32 v168, v170, v171
	v_cvt_pk_bf16_f32 v169, v172, v173
	v_exp_f32_e32 v153, v153
	global_store_dwordx4 v[154:155], v[166:169], off offset:256 sc1 nt
	v_add_f32_e32 v138, 1.0, v138
	s_nop 0
	v_or_b32_e32 v166, 16, v152
	v_ashrrev_i32_e32 v167, 31, v166
	v_lshlrev_b64 v[170:171], 10, v[166:167]
	v_rcp_f32_e32 v166, v138
	v_add_f32_e32 v138, 1.0, v151
	v_mul_f32_e32 v151, 0xbfb8aa3b, v121
	v_rcp_f32_e32 v167, v138
	v_add_f32_e32 v138, 1.0, v153
	v_exp_f32_e32 v151, v151
	v_mul_f32_e32 v153, 0xbfb8aa3b, v114
	v_exp_f32_e32 v153, v153
	v_rcp_f32_e32 v168, v138
	v_add_f32_e32 v138, 1.0, v151
	v_rcp_f32_e32 v169, v138
	v_add_f32_e32 v138, 1.0, v153
	v_mul_f32_e32 v151, 0xbfb8aa3b, v116
	v_rcp_f32_e32 v172, v138
	v_mul_f32_e32 v138, 0xbfb8aa3b, v115
	v_exp_f32_e32 v151, v151
	v_mul_f32_e32 v153, 0xbfb8aa3b, v117
	v_exp_f32_e32 v138, v138
	v_exp_f32_e32 v153, v153
	v_add_f32_e32 v151, 1.0, v151
	v_rcp_f32_e32 v174, v151
	v_add_f32_e32 v138, 1.0, v138
	v_add_f32_e32 v151, 1.0, v153
	v_rcp_f32_e32 v175, v151
	v_rcp_f32_e32 v173, v138
	v_mul_f32_e32 v138, 0xbfb8aa3b, v94
	v_exp_f32_e32 v138, v138
	v_mul_f32_e32 v151, 0xbfb8aa3b, v95
	v_exp_f32_e32 v151, v151
	v_mul_f32_e32 v153, 0xbfb8aa3b, v96
	v_exp_f32_e32 v153, v153
	v_pk_mul_f32 v[168:169], v[120:121], v[168:169]
	v_pk_mul_f32 v[166:167], v[118:119], v[166:167]
	v_pk_mul_f32 v[174:175], v[116:117], v[174:175]
	v_pk_mul_f32 v[172:173], v[114:115], v[172:173]
	v_lshl_add_u64 v[170:171], s[8:9], 0, v[170:171]
	v_cvt_pk_bf16_f32 v166, v166, v167
	v_cvt_pk_bf16_f32 v167, v168, v169
	v_cvt_pk_bf16_f32 v168, v172, v173
	v_cvt_pk_bf16_f32 v169, v174, v175
	v_lshl_add_u64 v[170:171], v[170:171], 0, v[156:157]
	v_add_f32_e32 v138, 1.0, v138
	global_store_dwordx4 v[170:171], v[166:169], off sc1 nt
	s_nop 1
	v_rcp_f32_e32 v166, v138
	v_add_f32_e32 v138, 1.0, v151
	v_mul_f32_e32 v151, 0xbfb8aa3b, v97
	v_rcp_f32_e32 v167, v138
	v_add_f32_e32 v138, 1.0, v153
	v_exp_f32_e32 v151, v151
	v_mul_f32_e32 v153, 0xbfb8aa3b, v90
	v_exp_f32_e32 v153, v153
	v_rcp_f32_e32 v168, v138
	v_add_f32_e32 v138, 1.0, v151
	v_rcp_f32_e32 v169, v138
	v_add_f32_e32 v138, 1.0, v153
	v_mul_f32_e32 v151, 0xbfb8aa3b, v92
	v_rcp_f32_e32 v172, v138
	v_mul_f32_e32 v138, 0xbfb8aa3b, v91
	v_exp_f32_e32 v151, v151
	v_mul_f32_e32 v153, 0xbfb8aa3b, v93
	v_exp_f32_e32 v138, v138
	v_exp_f32_e32 v153, v153
	v_add_f32_e32 v151, 1.0, v151
	v_rcp_f32_e32 v174, v151
	v_add_f32_e32 v138, 1.0, v138
	v_add_f32_e32 v151, 1.0, v153
	v_rcp_f32_e32 v175, v151
	v_rcp_f32_e32 v173, v138
	v_mul_f32_e32 v138, 0xbfb8aa3b, v102
	v_exp_f32_e32 v138, v138
	v_mul_f32_e32 v151, 0xbfb8aa3b, v103
	v_pk_mul_f32 v[168:169], v[96:97], v[168:169]
	v_pk_mul_f32 v[166:167], v[94:95], v[166:167]
	v_pk_mul_f32 v[174:175], v[92:93], v[174:175]
	v_pk_mul_f32 v[172:173], v[90:91], v[172:173]
	v_exp_f32_e32 v151, v151
	v_mul_f32_e32 v153, 0xbfb8aa3b, v104
	v_cvt_pk_bf16_f32 v166, v166, v167
	v_cvt_pk_bf16_f32 v167, v168, v169
	v_cvt_pk_bf16_f32 v168, v172, v173
	v_cvt_pk_bf16_f32 v169, v174, v175
	v_exp_f32_e32 v153, v153
	global_store_dwordx4 v[170:171], v[166:169], off offset:256 sc1 nt
	v_add_f32_e32 v138, 1.0, v138
	s_nop 0
	v_or_b32_e32 v166, 32, v152
	v_ashrrev_i32_e32 v167, 31, v166
	v_lshlrev_b64 v[170:171], 10, v[166:167]
	v_rcp_f32_e32 v166, v138
	v_add_f32_e32 v138, 1.0, v151
	v_mul_f32_e32 v151, 0xbfb8aa3b, v105
	v_rcp_f32_e32 v167, v138
	v_add_f32_e32 v138, 1.0, v153
	v_exp_f32_e32 v151, v151
	v_mul_f32_e32 v153, 0xbfb8aa3b, v98
	v_exp_f32_e32 v153, v153
	v_rcp_f32_e32 v168, v138
	v_add_f32_e32 v138, 1.0, v151
	v_rcp_f32_e32 v169, v138
	v_add_f32_e32 v138, 1.0, v153
	v_mul_f32_e32 v151, 0xbfb8aa3b, v100
	v_rcp_f32_e32 v172, v138
	v_mul_f32_e32 v138, 0xbfb8aa3b, v99
	v_exp_f32_e32 v151, v151
	v_mul_f32_e32 v153, 0xbfb8aa3b, v101
	v_exp_f32_e32 v138, v138
	v_exp_f32_e32 v153, v153
	v_add_f32_e32 v151, 1.0, v151
	v_rcp_f32_e32 v174, v151
	v_add_f32_e32 v138, 1.0, v138
	v_add_f32_e32 v151, 1.0, v153
	v_rcp_f32_e32 v175, v151
	v_rcp_f32_e32 v173, v138
	v_mul_f32_e32 v138, 0xbfb8aa3b, v78
	v_exp_f32_e32 v138, v138
	v_mul_f32_e32 v151, 0xbfb8aa3b, v79
	v_exp_f32_e32 v151, v151
	v_mul_f32_e32 v153, 0xbfb8aa3b, v80
	v_exp_f32_e32 v153, v153
	v_pk_mul_f32 v[168:169], v[104:105], v[168:169]
	v_pk_mul_f32 v[166:167], v[102:103], v[166:167]
	v_pk_mul_f32 v[174:175], v[100:101], v[174:175]
	v_pk_mul_f32 v[172:173], v[98:99], v[172:173]
	v_lshl_add_u64 v[170:171], s[8:9], 0, v[170:171]
	v_cvt_pk_bf16_f32 v166, v166, v167
	v_cvt_pk_bf16_f32 v167, v168, v169
	v_cvt_pk_bf16_f32 v168, v172, v173
	v_cvt_pk_bf16_f32 v169, v174, v175
	v_lshl_add_u64 v[170:171], v[170:171], 0, v[156:157]
	v_add_f32_e32 v138, 1.0, v138
	global_store_dwordx4 v[170:171], v[166:169], off sc1 nt
	s_nop 1
	v_rcp_f32_e32 v166, v138
	v_add_f32_e32 v138, 1.0, v151
	v_mul_f32_e32 v151, 0xbfb8aa3b, v81
	v_rcp_f32_e32 v167, v138
	v_add_f32_e32 v138, 1.0, v153
	v_exp_f32_e32 v151, v151
	v_mul_f32_e32 v153, 0xbfb8aa3b, v74
	v_exp_f32_e32 v153, v153
	v_rcp_f32_e32 v168, v138
	v_add_f32_e32 v138, 1.0, v151
	v_rcp_f32_e32 v169, v138
	v_add_f32_e32 v138, 1.0, v153
	v_mul_f32_e32 v151, 0xbfb8aa3b, v76
	v_rcp_f32_e32 v172, v138
	v_mul_f32_e32 v138, 0xbfb8aa3b, v75
	v_exp_f32_e32 v151, v151
	v_mul_f32_e32 v153, 0xbfb8aa3b, v77
	v_exp_f32_e32 v138, v138
	v_exp_f32_e32 v153, v153
	v_add_f32_e32 v151, 1.0, v151
	v_rcp_f32_e32 v174, v151
	v_add_f32_e32 v138, 1.0, v138
	v_add_f32_e32 v151, 1.0, v153
	v_rcp_f32_e32 v175, v151
	v_rcp_f32_e32 v173, v138
	v_mul_f32_e32 v138, 0xbfb8aa3b, v86
	v_exp_f32_e32 v138, v138
	v_mul_f32_e32 v151, 0xbfb8aa3b, v87
	v_pk_mul_f32 v[168:169], v[80:81], v[168:169]
	v_pk_mul_f32 v[166:167], v[78:79], v[166:167]
	v_pk_mul_f32 v[174:175], v[76:77], v[174:175]
	v_pk_mul_f32 v[172:173], v[74:75], v[172:173]
	v_exp_f32_e32 v151, v151
	v_mul_f32_e32 v153, 0xbfb8aa3b, v88
	v_cvt_pk_bf16_f32 v166, v166, v167
	v_cvt_pk_bf16_f32 v167, v168, v169
	v_cvt_pk_bf16_f32 v168, v172, v173
	v_cvt_pk_bf16_f32 v169, v174, v175
	v_exp_f32_e32 v153, v153
	global_store_dwordx4 v[170:171], v[166:169], off offset:256 sc1 nt
	v_add_f32_e32 v138, 1.0, v138
	s_nop 0
	v_or_b32_e32 v166, 48, v152
	v_ashrrev_i32_e32 v167, 31, v166
	v_lshlrev_b64 v[170:171], 10, v[166:167]
	v_rcp_f32_e32 v166, v138
	v_add_f32_e32 v138, 1.0, v151
	v_mul_f32_e32 v151, 0xbfb8aa3b, v89
	v_rcp_f32_e32 v167, v138
	v_add_f32_e32 v138, 1.0, v153
	v_exp_f32_e32 v151, v151
	v_mul_f32_e32 v153, 0xbfb8aa3b, v82
	v_exp_f32_e32 v153, v153
	v_rcp_f32_e32 v168, v138
	v_add_f32_e32 v138, 1.0, v151
	v_rcp_f32_e32 v169, v138
	v_add_f32_e32 v138, 1.0, v153
	v_mul_f32_e32 v151, 0xbfb8aa3b, v84
	v_rcp_f32_e32 v172, v138
	v_mul_f32_e32 v138, 0xbfb8aa3b, v83
	v_exp_f32_e32 v151, v151
	v_mul_f32_e32 v153, 0xbfb8aa3b, v85
	v_exp_f32_e32 v138, v138
	v_exp_f32_e32 v153, v153
	v_add_f32_e32 v151, 1.0, v151
	v_rcp_f32_e32 v174, v151
	v_add_f32_e32 v138, 1.0, v138
	v_add_f32_e32 v151, 1.0, v153
	v_rcp_f32_e32 v175, v151
	v_rcp_f32_e32 v173, v138
	v_mul_f32_e32 v138, 0xbfb8aa3b, v70
	v_exp_f32_e32 v138, v138
	v_mul_f32_e32 v151, 0xbfb8aa3b, v71
	v_exp_f32_e32 v151, v151
	v_mul_f32_e32 v153, 0xbfb8aa3b, v72
	v_exp_f32_e32 v153, v153
	v_pk_mul_f32 v[168:169], v[88:89], v[168:169]
	v_pk_mul_f32 v[166:167], v[86:87], v[166:167]
	v_pk_mul_f32 v[174:175], v[84:85], v[174:175]
	v_pk_mul_f32 v[172:173], v[82:83], v[172:173]
	v_lshl_add_u64 v[170:171], s[8:9], 0, v[170:171]
	v_cvt_pk_bf16_f32 v166, v166, v167
	v_cvt_pk_bf16_f32 v167, v168, v169
	v_cvt_pk_bf16_f32 v168, v172, v173
	v_cvt_pk_bf16_f32 v169, v174, v175
	v_lshl_add_u64 v[156:157], v[170:171], 0, v[156:157]
	v_add_f32_e32 v138, 1.0, v138
	global_store_dwordx4 v[156:157], v[166:169], off sc1 nt
	s_nop 1
	v_rcp_f32_e32 v166, v138
	v_add_f32_e32 v138, 1.0, v151
	v_mul_f32_e32 v151, 0xbfb8aa3b, v73
	v_rcp_f32_e32 v167, v138
	v_add_f32_e32 v138, 1.0, v153
	v_exp_f32_e32 v151, v151
	v_mul_f32_e32 v153, 0xbfb8aa3b, v66
	v_exp_f32_e32 v153, v153
	v_rcp_f32_e32 v168, v138
	v_add_f32_e32 v138, 1.0, v151
	v_rcp_f32_e32 v169, v138
	v_add_f32_e32 v138, 1.0, v153
	v_mul_f32_e32 v151, 0xbfb8aa3b, v68
	v_rcp_f32_e32 v170, v138
	v_mul_f32_e32 v138, 0xbfb8aa3b, v67
	v_exp_f32_e32 v151, v151
	v_mul_f32_e32 v153, 0xbfb8aa3b, v69
	v_exp_f32_e32 v138, v138
	v_exp_f32_e32 v153, v153
	v_add_f32_e32 v151, 1.0, v151
	v_rcp_f32_e32 v172, v151
	v_add_f32_e32 v138, 1.0, v138
	v_add_f32_e32 v151, 1.0, v153
	v_rcp_f32_e32 v173, v151
	v_rcp_f32_e32 v171, v138
	v_mul_f32_e32 v138, 0xbfb8aa3b, v62
	v_exp_f32_e32 v138, v138
	v_mul_f32_e32 v151, 0xbfb8aa3b, v63
	v_exp_f32_e32 v151, v151
	v_mul_f32_e32 v153, 0xbfb8aa3b, v64
	v_exp_f32_e32 v153, v153
	v_pk_mul_f32 v[168:169], v[72:73], v[168:169]
	v_pk_mul_f32 v[166:167], v[70:71], v[166:167]
	v_pk_mul_f32 v[172:173], v[68:69], v[172:173]
	v_pk_mul_f32 v[170:171], v[66:67], v[170:171]
	v_cvt_pk_bf16_f32 v166, v166, v167
	v_cvt_pk_bf16_f32 v167, v168, v169
	v_cvt_pk_bf16_f32 v168, v170, v171
	v_cvt_pk_bf16_f32 v169, v172, v173
	v_add_f32_e32 v138, 1.0, v138
	global_store_dwordx4 v[156:157], v[166:169], off offset:256 sc1 nt
	v_rcp_f32_e32 v156, v138
	v_add_f32_e32 v138, 1.0, v151
	v_mul_f32_e32 v151, 0xbfb8aa3b, v65
	v_rcp_f32_e32 v157, v138
	v_add_f32_e32 v138, 1.0, v153
	v_exp_f32_e32 v151, v151
	v_mul_f32_e32 v153, 0xbfb8aa3b, v58
	v_exp_f32_e32 v153, v153
	v_rcp_f32_e32 v166, v138
	v_add_f32_e32 v138, 1.0, v151
	v_rcp_f32_e32 v167, v138
	v_add_f32_e32 v138, 1.0, v153
	v_mul_f32_e32 v151, 0xbfb8aa3b, v60
	v_rcp_f32_e32 v168, v138
	v_mul_f32_e32 v138, 0xbfb8aa3b, v59
	v_exp_f32_e32 v151, v151
	v_mul_f32_e32 v153, 0xbfb8aa3b, v61
	v_exp_f32_e32 v138, v138
	v_exp_f32_e32 v153, v153
	v_add_f32_e32 v151, 1.0, v151
	v_rcp_f32_e32 v170, v151
	v_add_f32_e32 v138, 1.0, v138
	v_add_f32_e32 v151, 1.0, v153
	v_rcp_f32_e32 v171, v151
	v_rcp_f32_e32 v169, v138
	v_mul_f32_e32 v138, 0xbfb8aa3b, v46
	v_exp_f32_e32 v138, v138
	v_mul_f32_e32 v151, 0xbfb8aa3b, v47
	v_pk_mul_f32 v[156:157], v[62:63], v[156:157]
	v_exp_f32_e32 v151, v151
	v_mul_f32_e32 v153, 0xbfb8aa3b, v48
	v_pk_mul_f32 v[172:173], v[64:65], v[166:167]
	v_pk_mul_f32 v[170:171], v[60:61], v[170:171]
	v_pk_mul_f32 v[168:169], v[58:59], v[168:169]
	v_cvt_pk_bf16_f32 v166, v156, v157
	v_lshl_add_u64 v[156:157], v[154:155], 0, s[18:19]
	s_mov_b32 s18, 0x20000
	v_exp_f32_e32 v153, v153
	v_cvt_pk_bf16_f32 v168, v168, v169
	v_cvt_pk_bf16_f32 v169, v170, v171
	v_add_co_u32_e32 v170, vcc, s18, v154
	v_cvt_pk_bf16_f32 v167, v172, v173
	s_nop 0
	v_addc_co_u32_e32 v171, vcc, 0, v155, vcc
	v_add_f32_e32 v138, 1.0, v138
	global_store_dwordx4 v[170:171], v[166:169], off sc1 nt
	s_mov_b64 s[18:19], 0x24000
	s_nop 0
	v_rcp_f32_e32 v166, v138
	v_add_f32_e32 v138, 1.0, v151
	v_mul_f32_e32 v151, 0xbfb8aa3b, v49
	v_rcp_f32_e32 v167, v138
	v_add_f32_e32 v138, 1.0, v153
	v_exp_f32_e32 v151, v151
	v_mul_f32_e32 v153, 0xbfb8aa3b, v42
	v_exp_f32_e32 v153, v153
	v_rcp_f32_e32 v168, v138
	v_add_f32_e32 v138, 1.0, v151
	v_rcp_f32_e32 v169, v138
	v_add_f32_e32 v138, 1.0, v153
	v_mul_f32_e32 v151, 0xbfb8aa3b, v44
	v_rcp_f32_e32 v170, v138
	v_mul_f32_e32 v138, 0xbfb8aa3b, v43
	v_exp_f32_e32 v151, v151
	v_mul_f32_e32 v153, 0xbfb8aa3b, v45
	v_exp_f32_e32 v138, v138
	v_exp_f32_e32 v153, v153
	v_add_f32_e32 v151, 1.0, v151
	v_rcp_f32_e32 v172, v151
	v_add_f32_e32 v138, 1.0, v138
	v_add_f32_e32 v151, 1.0, v153
	v_rcp_f32_e32 v173, v151
	v_rcp_f32_e32 v171, v138
	v_mul_f32_e32 v138, 0xbfb8aa3b, v54
	v_exp_f32_e32 v138, v138
	v_mul_f32_e32 v151, 0xbfb8aa3b, v55
	v_exp_f32_e32 v151, v151
	v_mul_f32_e32 v153, 0xbfb8aa3b, v56
	v_exp_f32_e32 v153, v153
	v_pk_mul_f32 v[168:169], v[48:49], v[168:169]
	v_pk_mul_f32 v[166:167], v[46:47], v[166:167]
	v_pk_mul_f32 v[172:173], v[44:45], v[172:173]
	v_pk_mul_f32 v[170:171], v[42:43], v[170:171]
	v_cvt_pk_bf16_f32 v166, v166, v167
	v_cvt_pk_bf16_f32 v167, v168, v169
	v_cvt_pk_bf16_f32 v168, v170, v171
	v_cvt_pk_bf16_f32 v169, v172, v173
	v_add_f32_e32 v138, 1.0, v138
	global_store_dwordx4 v[156:157], v[166:169], off offset:256 sc1 nt
	v_rcp_f32_e32 v156, v138
	v_add_f32_e32 v138, 1.0, v151
	v_mul_f32_e32 v151, 0xbfb8aa3b, v57
	v_rcp_f32_e32 v157, v138
	v_add_f32_e32 v138, 1.0, v153
	v_exp_f32_e32 v151, v151
	v_mul_f32_e32 v153, 0xbfb8aa3b, v50
	v_exp_f32_e32 v153, v153
	v_rcp_f32_e32 v166, v138
	v_add_f32_e32 v138, 1.0, v151
	v_rcp_f32_e32 v167, v138
	v_add_f32_e32 v138, 1.0, v153
	v_mul_f32_e32 v151, 0xbfb8aa3b, v52
	v_rcp_f32_e32 v168, v138
	v_mul_f32_e32 v138, 0xbfb8aa3b, v51
	v_exp_f32_e32 v151, v151
	v_mul_f32_e32 v153, 0xbfb8aa3b, v53
	v_exp_f32_e32 v138, v138
	v_exp_f32_e32 v153, v153
	v_add_f32_e32 v151, 1.0, v151
	v_rcp_f32_e32 v170, v151
	v_add_f32_e32 v138, 1.0, v138
	v_add_f32_e32 v151, 1.0, v153
	v_rcp_f32_e32 v171, v151
	v_rcp_f32_e32 v169, v138
	v_mul_f32_e32 v138, 0xbfb8aa3b, v30
	v_exp_f32_e32 v138, v138
	v_mul_f32_e32 v151, 0xbfb8aa3b, v31
	v_pk_mul_f32 v[156:157], v[54:55], v[156:157]
	v_exp_f32_e32 v151, v151
	v_mul_f32_e32 v153, 0xbfb8aa3b, v32
	v_pk_mul_f32 v[172:173], v[56:57], v[166:167]
	v_pk_mul_f32 v[170:171], v[52:53], v[170:171]
	v_pk_mul_f32 v[168:169], v[50:51], v[168:169]
	v_cvt_pk_bf16_f32 v166, v156, v157
	v_lshl_add_u64 v[156:157], v[154:155], 0, s[18:19]
	s_mov_b32 s18, 0x24000
	v_exp_f32_e32 v153, v153
	v_cvt_pk_bf16_f32 v168, v168, v169
	v_cvt_pk_bf16_f32 v169, v170, v171
	v_add_co_u32_e32 v170, vcc, s18, v154
	v_cvt_pk_bf16_f32 v167, v172, v173
	s_nop 0
	v_addc_co_u32_e32 v171, vcc, 0, v155, vcc
	v_add_f32_e32 v138, 1.0, v138
	global_store_dwordx4 v[170:171], v[166:169], off sc1 nt
	s_mov_b64 s[18:19], 0x28000
	s_nop 0
	v_rcp_f32_e32 v166, v138
	v_add_f32_e32 v138, 1.0, v151
	v_mul_f32_e32 v151, 0xbfb8aa3b, v33
	v_rcp_f32_e32 v167, v138
	v_add_f32_e32 v138, 1.0, v153
	v_exp_f32_e32 v151, v151
	v_mul_f32_e32 v153, 0xbfb8aa3b, v26
	v_exp_f32_e32 v153, v153
	v_rcp_f32_e32 v168, v138
	v_add_f32_e32 v138, 1.0, v151
	v_rcp_f32_e32 v169, v138
	v_add_f32_e32 v138, 1.0, v153
	v_mul_f32_e32 v151, 0xbfb8aa3b, v28
	v_rcp_f32_e32 v170, v138
	v_mul_f32_e32 v138, 0xbfb8aa3b, v27
	v_exp_f32_e32 v151, v151
	v_mul_f32_e32 v153, 0xbfb8aa3b, v29
	v_exp_f32_e32 v138, v138
	v_exp_f32_e32 v153, v153
	v_add_f32_e32 v151, 1.0, v151
	v_rcp_f32_e32 v172, v151
	v_add_f32_e32 v138, 1.0, v138
	v_add_f32_e32 v151, 1.0, v153
	v_rcp_f32_e32 v173, v151
	v_rcp_f32_e32 v171, v138
	v_mul_f32_e32 v138, 0xbfb8aa3b, v38
	v_exp_f32_e32 v138, v138
	v_mul_f32_e32 v151, 0xbfb8aa3b, v39
	v_exp_f32_e32 v151, v151
	v_mul_f32_e32 v153, 0xbfb8aa3b, v40
	v_exp_f32_e32 v153, v153
	v_pk_mul_f32 v[168:169], v[32:33], v[168:169]
	v_pk_mul_f32 v[166:167], v[30:31], v[166:167]
	v_pk_mul_f32 v[172:173], v[28:29], v[172:173]
	v_pk_mul_f32 v[170:171], v[26:27], v[170:171]
	v_cvt_pk_bf16_f32 v166, v166, v167
	v_cvt_pk_bf16_f32 v167, v168, v169
	v_cvt_pk_bf16_f32 v168, v170, v171
	v_cvt_pk_bf16_f32 v169, v172, v173
	v_add_f32_e32 v138, 1.0, v138
	global_store_dwordx4 v[156:157], v[166:169], off offset:256 sc1 nt
	v_rcp_f32_e32 v156, v138
	v_add_f32_e32 v138, 1.0, v151
	v_mul_f32_e32 v151, 0xbfb8aa3b, v41
	v_rcp_f32_e32 v157, v138
	v_add_f32_e32 v138, 1.0, v153
	v_exp_f32_e32 v151, v151
	v_mul_f32_e32 v153, 0xbfb8aa3b, v34
	v_exp_f32_e32 v153, v153
	v_rcp_f32_e32 v166, v138
	v_add_f32_e32 v138, 1.0, v151
	v_rcp_f32_e32 v167, v138
	v_add_f32_e32 v138, 1.0, v153
	v_mul_f32_e32 v151, 0xbfb8aa3b, v36
	v_rcp_f32_e32 v168, v138
	v_mul_f32_e32 v138, 0xbfb8aa3b, v35
	v_exp_f32_e32 v151, v151
	v_mul_f32_e32 v153, 0xbfb8aa3b, v37
	v_exp_f32_e32 v138, v138
	v_exp_f32_e32 v153, v153
	v_add_f32_e32 v151, 1.0, v151
	v_rcp_f32_e32 v170, v151
	v_add_f32_e32 v138, 1.0, v138
	v_add_f32_e32 v151, 1.0, v153
	v_rcp_f32_e32 v171, v151
	v_rcp_f32_e32 v169, v138
	v_mul_f32_e32 v138, 0xbfb8aa3b, v14
	v_exp_f32_e32 v138, v138
	v_mul_f32_e32 v151, 0xbfb8aa3b, v15
	v_pk_mul_f32 v[156:157], v[38:39], v[156:157]
	v_exp_f32_e32 v151, v151
	v_mul_f32_e32 v153, 0xbfb8aa3b, v16
	v_pk_mul_f32 v[172:173], v[40:41], v[166:167]
	v_pk_mul_f32 v[170:171], v[36:37], v[170:171]
	v_pk_mul_f32 v[168:169], v[34:35], v[168:169]
	v_cvt_pk_bf16_f32 v166, v156, v157
	v_lshl_add_u64 v[156:157], v[154:155], 0, s[18:19]
	s_mov_b32 s18, 0x28000
	v_exp_f32_e32 v153, v153
	v_cvt_pk_bf16_f32 v168, v168, v169
	v_cvt_pk_bf16_f32 v169, v170, v171
	v_add_co_u32_e32 v170, vcc, s18, v154
	v_cvt_pk_bf16_f32 v167, v172, v173
	s_nop 0
	v_addc_co_u32_e32 v171, vcc, 0, v155, vcc
	v_add_f32_e32 v138, 1.0, v138
	global_store_dwordx4 v[170:171], v[166:169], off sc1 nt
	s_mov_b64 s[18:19], 0x2c000
	s_nop 0
	v_rcp_f32_e32 v166, v138
	v_add_f32_e32 v138, 1.0, v151
	v_mul_f32_e32 v151, 0xbfb8aa3b, v17
	v_rcp_f32_e32 v167, v138
	v_add_f32_e32 v138, 1.0, v153
	v_exp_f32_e32 v151, v151
	v_mul_f32_e32 v153, 0xbfb8aa3b, v10
	v_exp_f32_e32 v153, v153
	v_rcp_f32_e32 v168, v138
	v_add_f32_e32 v138, 1.0, v151
	v_rcp_f32_e32 v169, v138
	v_add_f32_e32 v138, 1.0, v153
	v_mul_f32_e32 v151, 0xbfb8aa3b, v12
	v_rcp_f32_e32 v170, v138
	v_mul_f32_e32 v138, 0xbfb8aa3b, v11
	v_exp_f32_e32 v151, v151
	v_mul_f32_e32 v153, 0xbfb8aa3b, v13
	v_exp_f32_e32 v138, v138
	v_exp_f32_e32 v153, v153
	v_add_f32_e32 v151, 1.0, v151
	v_rcp_f32_e32 v172, v151
	v_add_f32_e32 v138, 1.0, v138
	v_add_f32_e32 v151, 1.0, v153
	v_rcp_f32_e32 v173, v151
	v_rcp_f32_e32 v171, v138
	v_mul_f32_e32 v138, 0xbfb8aa3b, v22
	v_exp_f32_e32 v138, v138
	v_mul_f32_e32 v151, 0xbfb8aa3b, v23
	v_exp_f32_e32 v151, v151
	v_mul_f32_e32 v153, 0xbfb8aa3b, v24
	v_exp_f32_e32 v153, v153
	v_pk_mul_f32 v[168:169], v[16:17], v[168:169]
	v_pk_mul_f32 v[166:167], v[14:15], v[166:167]
	v_pk_mul_f32 v[172:173], v[12:13], v[172:173]
	v_pk_mul_f32 v[170:171], v[10:11], v[170:171]
	v_cvt_pk_bf16_f32 v166, v166, v167
	v_cvt_pk_bf16_f32 v167, v168, v169
	v_cvt_pk_bf16_f32 v168, v170, v171
	v_cvt_pk_bf16_f32 v169, v172, v173
	v_add_f32_e32 v138, 1.0, v138
	global_store_dwordx4 v[156:157], v[166:169], off offset:256 sc1 nt
	v_rcp_f32_e32 v156, v138
	v_add_f32_e32 v138, 1.0, v151
	v_mul_f32_e32 v151, 0xbfb8aa3b, v25
	v_rcp_f32_e32 v157, v138
	v_add_f32_e32 v138, 1.0, v153
	v_exp_f32_e32 v151, v151
	v_mul_f32_e32 v153, 0xbfb8aa3b, v18
	v_exp_f32_e32 v153, v153
	v_rcp_f32_e32 v166, v138
	v_add_f32_e32 v138, 1.0, v151
	v_rcp_f32_e32 v167, v138
	v_add_f32_e32 v138, 1.0, v153
	v_mul_f32_e32 v151, 0xbfb8aa3b, v20
	v_rcp_f32_e32 v168, v138
	v_mul_f32_e32 v138, 0xbfb8aa3b, v19
	v_exp_f32_e32 v151, v151
	v_mul_f32_e32 v153, 0xbfb8aa3b, v21
	v_exp_f32_e32 v138, v138
	v_exp_f32_e32 v153, v153
	v_add_f32_e32 v151, 1.0, v151
	v_rcp_f32_e32 v170, v151
	v_add_f32_e32 v138, 1.0, v138
	v_add_f32_e32 v151, 1.0, v153
	v_rcp_f32_e32 v171, v151
	v_rcp_f32_e32 v169, v138
	v_mul_f32_e32 v138, 0xbfb8aa3b, v6
	v_exp_f32_e32 v138, v138
	v_mul_f32_e32 v151, 0xbfb8aa3b, v7
	v_pk_mul_f32 v[170:171], v[20:21], v[170:171]
	v_pk_mul_f32 v[168:169], v[18:19], v[168:169]
	v_exp_f32_e32 v151, v151
	v_mul_f32_e32 v153, 0xbfb8aa3b, v8
	v_cvt_pk_bf16_f32 v168, v168, v169
	v_cvt_pk_bf16_f32 v169, v170, v171
	v_lshl_add_u64 v[170:171], v[154:155], 0, s[18:19]
	s_mov_b32 s18, 0x2c000
	v_exp_f32_e32 v153, v153
	v_pk_mul_f32 v[172:173], v[24:25], v[166:167]
	v_pk_mul_f32 v[156:157], v[22:23], v[156:157]
	v_add_co_u32_e32 v154, vcc, s18, v154
	v_cvt_pk_bf16_f32 v166, v156, v157
	v_cvt_pk_bf16_f32 v167, v172, v173
	v_addc_co_u32_e32 v155, vcc, 0, v155, vcc
	v_add_f32_e32 v138, 1.0, v138
	global_store_dwordx4 v[154:155], v[166:169], off sc1 nt
	v_rcp_f32_e32 v154, v138
	v_add_f32_e32 v138, 1.0, v151
	v_mul_f32_e32 v151, 0xbfb8aa3b, v9
	v_rcp_f32_e32 v155, v138
	v_add_f32_e32 v138, 1.0, v153
	v_exp_f32_e32 v151, v151
	v_mul_f32_e32 v153, 0xbfb8aa3b, v2
	v_exp_f32_e32 v153, v153
	v_rcp_f32_e32 v156, v138
	v_add_f32_e32 v138, 1.0, v151
	v_rcp_f32_e32 v157, v138
	v_add_f32_e32 v138, 1.0, v153
	v_mul_f32_e32 v151, 0xbfb8aa3b, v4
	v_rcp_f32_e32 v166, v138
	v_mul_f32_e32 v138, 0xbfb8aa3b, v3
	v_exp_f32_e32 v151, v151
	v_mul_f32_e32 v153, 0xbfb8aa3b, v5
	v_exp_f32_e32 v138, v138
	v_exp_f32_e32 v153, v153
	v_add_f32_e32 v151, 1.0, v151
	v_rcp_f32_e32 v168, v151
	v_add_f32_e32 v138, 1.0, v138
	v_add_f32_e32 v151, 1.0, v153
	v_rcp_f32_e32 v169, v151
	v_rcp_f32_e32 v167, v138
	v_pk_mul_f32 v[156:157], v[8:9], v[156:157]
	v_pk_mul_f32 v[154:155], v[6:7], v[154:155]
	v_pk_mul_f32 v[168:169], v[4:5], v[168:169]
	v_pk_mul_f32 v[166:167], v[2:3], v[166:167]
	v_cvt_pk_bf16_f32 v154, v154, v155
	v_cvt_pk_bf16_f32 v155, v156, v157
	v_cvt_pk_bf16_f32 v156, v166, v167
	v_cvt_pk_bf16_f32 v157, v168, v169
	global_store_dwordx4 v[170:171], v[154:157], off offset:256 sc1 nt

.LBB0_182:
	s_ashr_i32 s21, s17, 5
	v_lshl_or_b32 v153, s88, 13, v162
	v_cvt_pk_bf16_f32 v126, v126, v127
	v_cvt_pk_bf16_f32 v127, v128, v129
	v_cvt_pk_bf16_f32 v128, v122, v123
	v_add_u32_e32 v122, s21, v153
	v_cvt_pk_bf16_f32 v129, v124, v125
	v_mad_i64_i32 v[122:123], s[18:19], v122, s87, v[140:141]
	global_store_dwordx4 v[122:123], v[126:129], off sc1 nt
	v_cvt_pk_bf16_f32 v110, v110, v111
	v_cvt_pk_bf16_f32 v111, v112, v113
	v_or_b32_e32 v126, 0x1000, v153
	v_cvt_pk_bf16_f32 v112, v106, v107
	v_add_u32_e32 v106, s21, v126
	v_mad_i64_i32 v[124:125], s[18:19], v106, s87, v[140:141]
	v_cvt_pk_bf16_f32 v94, v94, v95
	v_cvt_pk_bf16_f32 v95, v96, v97
	v_cvt_pk_bf16_f32 v96, v90, v91
	v_cvt_pk_bf16_f32 v97, v92, v93
	s_or_b32 s21, s21, 1
	global_store_dwordx4 v[124:125], v[94:97], off offset:512 sc1 nt
	v_cvt_pk_bf16_f32 v90, v102, v103
	v_cvt_pk_bf16_f32 v91, v104, v105
	v_add_u32_e32 v94, s21, v153
	v_cvt_pk_bf16_f32 v92, v98, v99
	v_cvt_pk_bf16_f32 v93, v100, v101
	v_mad_i64_i32 v[94:95], s[18:19], v94, s87, v[140:141]
	global_store_dwordx4 v[94:95], v[90:93], off sc1 nt
	v_cvt_pk_bf16_f32 v78, v78, v79
	v_cvt_pk_bf16_f32 v79, v80, v81
	v_cvt_pk_bf16_f32 v80, v74, v75
	v_add_u32_e32 v74, s21, v126
	v_or_b32_e32 v90, 48, v152
	v_cvt_pk_bf16_f32 v81, v76, v77
	v_mad_i64_i32 v[74:75], s[18:19], v74, s87, v[140:141]
	v_ashrrev_i32_e32 v91, 5, v90
	global_store_dwordx4 v[74:75], v[78:81], off sc1 nt
	v_cvt_pk_bf16_f32 v70, v70, v71
	v_cvt_pk_bf16_f32 v71, v72, v73
	v_add_u32_e32 v80, v91, v153
	v_mov_b64_e32 v[78:79], s[28:29]
	v_cvt_pk_bf16_f32 v72, v66, v67
	v_add_u32_e32 v66, v91, v126
	v_mad_i64_i32 v[80:81], s[18:19], v80, s87, v[78:79]
	v_mad_i64_i32 v[66:67], s[18:19], v66, s87, v[78:79]
	v_cvt_pk_bf16_f32 v76, v82, v83
	v_lshlrev_b32_e32 v82, 5, v90
	s_add_i32 s18, s17, 0x80
	v_and_b32_e32 v138, 0x3e0, v82
	s_ashr_i32 s21, s18, 5
	v_lshl_add_u64 v[80:81], v[80:81], 0, v[138:139]
	v_mov_b32_e32 v151, v139
	v_lshl_add_u64 v[66:67], v[66:67], 0, v[138:139]
	v_cvt_pk_bf16_f32 v46, v46, v47
	v_cvt_pk_bf16_f32 v47, v48, v49
	v_cvt_pk_bf16_f32 v48, v42, v43
	v_add_u32_e32 v42, s21, v126
	v_cvt_pk_bf16_f32 v113, v108, v109
	v_cvt_pk_bf16_f32 v106, v118, v119
	v_cvt_pk_bf16_f32 v107, v120, v121
	v_cvt_pk_bf16_f32 v108, v114, v115
	v_cvt_pk_bf16_f32 v109, v116, v117
	v_cvt_pk_bf16_f32 v74, v86, v87
	v_cvt_pk_bf16_f32 v75, v88, v89
	v_cvt_pk_bf16_f32 v77, v84, v85
	v_lshl_add_u64 v[80:81], v[80:81], 0, v[150:151]
	v_cvt_pk_bf16_f32 v73, v68, v69
	v_lshl_add_u64 v[66:67], v[66:67], 0, v[150:151]
	v_cvt_pk_bf16_f32 v49, v44, v45
	v_mad_i64_i32 v[42:43], s[18:19], v42, s87, v[140:141]
	global_store_dwordx4 v[124:125], v[110:113], off sc1 nt
	global_store_dwordx4 v[122:123], v[106:109], off offset:512 sc1 nt
	global_store_dwordx4 v[80:81], v[74:77], off sc1 nt
	global_store_dwordx4 v[66:67], v[70:73], off sc1 nt
	global_store_dwordx4 v[42:43], v[46:49], off sc1 nt
	v_cvt_pk_bf16_f32 v30, v30, v31
	v_cvt_pk_bf16_f32 v31, v32, v33
	v_add_u32_e32 v48, 0x90, v152
	v_ashrrev_i32_e32 v49, 5, v48
	v_add_u32_e32 v46, v49, v153
	v_lshlrev_b32_e32 v48, 5, v48
	v_cvt_pk_bf16_f32 v32, v26, v27
	v_add_u32_e32 v26, v49, v126
	s_addk_i32 s17, 0xa0
	v_mad_i64_i32 v[46:47], s[18:19], v46, s87, v[78:79]
	v_and_b32_e32 v138, 0x3e0, v48
	v_mad_i64_i32 v[26:27], s[18:19], v26, s87, v[78:79]
	s_ashr_i32 s17, s17, 5
	v_cvt_pk_bf16_f32 v62, v62, v63
	v_cvt_pk_bf16_f32 v63, v64, v65
	v_cvt_pk_bf16_f32 v64, v58, v59
	v_add_u32_e32 v58, s21, v153
	v_lshl_add_u64 v[46:47], v[46:47], 0, v[138:139]
	v_lshl_add_u64 v[26:27], v[26:27], 0, v[138:139]
	v_cvt_pk_bf16_f32 v14, v14, v15
	v_cvt_pk_bf16_f32 v15, v16, v17
	v_cvt_pk_bf16_f32 v16, v10, v11
	v_add_u32_e32 v10, s17, v126
	v_cvt_pk_bf16_f32 v65, v60, v61
	v_mad_i64_i32 v[58:59], s[18:19], v58, s87, v[140:141]
	v_cvt_pk_bf16_f32 v42, v54, v55
	v_cvt_pk_bf16_f32 v43, v56, v57
	v_cvt_pk_bf16_f32 v44, v50, v51
	v_cvt_pk_bf16_f32 v45, v52, v53
	v_lshl_add_u64 v[46:47], v[46:47], 0, v[150:151]
	v_cvt_pk_bf16_f32 v33, v28, v29
	v_lshl_add_u64 v[26:27], v[26:27], 0, v[150:151]
	v_cvt_pk_bf16_f32 v17, v12, v13
	v_mad_i64_i32 v[10:11], s[18:19], v10, s87, v[140:141]
	global_store_dwordx4 v[58:59], v[62:65], off sc1 nt
	global_store_dwordx4 v[46:47], v[42:45], off sc1 nt
	global_store_dwordx4 v[26:27], v[30:33], off sc1 nt
	global_store_dwordx4 v[10:11], v[14:17], off sc1 nt
	v_cvt_pk_bf16_f32 v6, v6, v7
	v_cvt_pk_bf16_f32 v7, v8, v9
	v_add_u32_e32 v16, 0xb0, v152
	v_ashrrev_i32_e32 v17, 5, v16
	v_add_u32_e32 v14, v17, v153
	v_lshlrev_b32_e32 v16, 5, v16
	v_cvt_pk_bf16_f32 v8, v2, v3
	v_add_u32_e32 v2, v17, v126
	v_mad_i64_i32 v[14:15], s[18:19], v14, s87, v[78:79]
	v_and_b32_e32 v138, 0x3e0, v16
	v_mad_i64_i32 v[2:3], s[18:19], v2, s87, v[78:79]
	v_add_u32_e32 v30, s17, v153
	v_lshl_add_u64 v[14:15], v[14:15], 0, v[138:139]
	v_lshl_add_u64 v[2:3], v[2:3], 0, v[138:139]
	v_cvt_pk_bf16_f32 v26, v38, v39
	v_cvt_pk_bf16_f32 v27, v40, v41
	v_cvt_pk_bf16_f32 v28, v34, v35
	v_cvt_pk_bf16_f32 v29, v36, v37
	v_mad_i64_i32 v[30:31], s[18:19], v30, s87, v[140:141]
	v_cvt_pk_bf16_f32 v10, v22, v23
	v_cvt_pk_bf16_f32 v11, v24, v25
	v_cvt_pk_bf16_f32 v12, v18, v19
	v_cvt_pk_bf16_f32 v13, v20, v21
	v_lshl_add_u64 v[14:15], v[14:15], 0, v[150:151]
	v_cvt_pk_bf16_f32 v9, v4, v5
	v_lshl_add_u64 v[2:3], v[2:3], 0, v[150:151]
	global_store_dwordx4 v[30:31], v[26:29], off sc1 nt
	global_store_dwordx4 v[14:15], v[10:13], off sc1 nt
	global_store_dwordx4 v[2:3], v[6:9], off sc1 nt
	s_andn2_b64 vcc, exec, s[0:1]
	s_mov_b64 s[0:1], -1
	s_cbranch_vccnz .LBB0_159
